# v18_relu
# speedup vs baseline: 1.0010x; 1.0010x over previous
; #define MFMA16(a, b, c) __builtin_amdgcn_mfma_f32_16x16x32_bf16((a), (b), (c), 0, 0, 0)
; DI void indexer_item(const Params& p, int b, int qt16, char* smem) {
;     ...
;     for (int h = 0; h < 16; ++h) {
;       f32x4 acc[4];
; #pragma unroll
;       for (int t = 0; t < 4; ++t) acc[t] = f32x4{0.f, 0.f, 0.f, 0.f};
; #pragma unroll
;       for (int ks = 0; ks < 2; ++ks) {
;         const bf16x8 bq = *(const bf16x8*)(iqs + l15 * 1040 + h * 64 + ks * 32 + g4 * 8);
; #pragma unroll
;         for (int t = 0; t < 4; ++t) acc[t] = MFMA16(kf[t][ks], bq, acc[t]);
;       }
;       const float w = wls[l15 * 16 + h];
; #pragma unroll
;       for (int t = 0; t < 4; ++t)
; #pragma unroll
;         for (int i = 0; i < 4; ++i) isc[t][i] += fmaxf(acc[t][i], 0.f) * w;
;     }
.LBB0_320:
	ds_read_b128 v[82:85], v106
	ds_read_b128 v[116:119], v106 offset:64
	s_waitcnt lgkmcnt(1)
	v_mfma_f32_16x16x32_bf16 v[92:95], v[2:5], v[82:85], 0
	ds_read_b128 v[120:123], v106 offset:192
	v_mfma_f32_16x16x32_bf16 v[108:111], v[10:13], v[82:85], 0
	v_mfma_f32_16x16x32_bf16 v[112:115], v[18:21], v[82:85], 0
	v_mfma_f32_16x16x32_bf16 v[82:85], v[26:29], v[82:85], 0
	s_waitcnt lgkmcnt(1)
	v_mfma_f32_16x16x32_bf16 v[92:95], v[6:9], v[116:119], v[92:95]
	v_mfma_f32_16x16x32_bf16 v[108:111], v[14:17], v[116:119], v[108:111]
	v_mfma_f32_16x16x32_bf16 v[112:115], v[22:25], v[116:119], v[112:115]
	s_nop 5
	v_mfma_f32_16x16x32_bf16 v[116:119], v[30:33], v[116:119], v[82:85]
	v_max_f32_e32 v92, 0, v92
	v_max_f32_e32 v93, 0, v93
	s_nop 0
	v_add_u32_e32 v82, s0, v103
	ds_read_b128 v[82:85], v82
	v_max_f32_e32 v94, 0, v94
	v_max_f32_e32 v95, 0, v95
	s_add_i32 s0, s0, 16
	s_cmp_eq_u32 s0, 64
	s_waitcnt lgkmcnt(0)
	v_pk_fma_f32 v[66:67], v[92:93], v[82:83], v[66:67] op_sel_hi:[1,0,1]
	v_pk_fma_f32 v[92:93], v[94:95], v[82:83], v[68:69] op_sel_hi:[1,0,1]
	v_max_f32_e32 v68, 0, v108
	v_max_f32_e32 v69, 0, v109
	v_max_f32_e32 v94, 0, v110
	v_max_f32_e32 v95, 0, v111
	v_pk_fma_f32 v[68:69], v[68:69], v[82:83], v[70:71] op_sel_hi:[1,0,1]
	v_pk_fma_f32 v[94:95], v[94:95], v[82:83], v[72:73] op_sel_hi:[1,0,1]
	v_max_f32_e32 v70, 0, v112
	v_max_f32_e32 v71, 0, v113
	v_max_f32_e32 v72, 0, v114
	v_max_f32_e32 v73, 0, v115
	v_pk_fma_f32 v[70:71], v[82:83], v[70:71], v[74:75] op_sel_hi:[0,1,1]
	v_pk_fma_f32 v[74:75], v[82:83], v[72:73], v[76:77] op_sel_hi:[0,1,1]
	v_max_f32_e32 v72, 0, v116
	v_max_f32_e32 v73, 0, v117
	v_max_f32_e32 v76, 0, v118
	v_max_f32_e32 v77, 0, v119
	v_pk_fma_f32 v[72:73], v[82:83], v[72:73], v[78:79] op_sel_hi:[0,1,1]
	v_pk_fma_f32 v[76:77], v[82:83], v[76:77], v[80:81] op_sel_hi:[0,1,1]
	ds_read_b128 v[78:81], v106 offset:128
	s_waitcnt lgkmcnt(0)
	v_mfma_f32_16x16x32_bf16 v[108:111], v[2:5], v[78:81], 0
	v_mfma_f32_16x16x32_bf16 v[112:115], v[10:13], v[78:81], 0
	v_mfma_f32_16x16x32_bf16 v[116:119], v[18:21], v[78:81], 0
	v_mfma_f32_16x16x32_bf16 v[78:81], v[26:29], v[78:81], 0
	v_mfma_f32_16x16x32_bf16 v[108:111], v[6:9], v[120:123], v[108:111]
	v_mfma_f32_16x16x32_bf16 v[112:115], v[14:17], v[120:123], v[112:115]
	v_mfma_f32_16x16x32_bf16 v[116:119], v[22:25], v[120:123], v[116:119]
	s_nop 2
	v_mfma_f32_16x16x32_bf16 v[120:123], v[30:33], v[120:123], v[78:81]
	s_nop 4
	v_max_f32_e32 v80, 0, v108
	v_max_f32_e32 v81, 0, v109
	v_max_f32_e32 v78, 0, v110
	v_max_f32_e32 v79, 0, v111
	v_pk_fma_f32 v[66:67], v[80:81], v[82:83], v[66:67] op_sel:[0,1,0]
	v_pk_fma_f32 v[78:79], v[78:79], v[82:83], v[92:93] op_sel:[0,1,0]
	v_max_f32_e32 v92, 0, v112
	v_max_f32_e32 v93, 0, v113
	v_pk_fma_f32 v[96:97], v[92:93], v[82:83], v[68:69] op_sel:[0,1,0]
	v_max_f32_e32 v68, 0, v116
	v_max_f32_e32 v69, 0, v117
	v_max_f32_e32 v92, 0, v118
	v_max_f32_e32 v93, 0, v119
	v_pk_fma_f32 v[92:93], v[82:83], v[92:93], v[74:75] op_sel:[1,0,0]
	v_pk_fma_f32 v[74:75], v[82:83], v[68:69], v[70:71] op_sel:[1,0,0]
	v_max_f32_e32 v80, 0, v114
	v_max_f32_e32 v81, 0, v115
	v_max_f32_e32 v68, 0, v120
	v_max_f32_e32 v69, 0, v121
	v_max_f32_e32 v70, 0, v122
	v_max_f32_e32 v71, 0, v123
	v_pk_fma_f32 v[80:81], v[80:81], v[82:83], v[94:95] op_sel:[0,1,0]
	v_pk_fma_f32 v[94:95], v[82:83], v[70:71], v[76:77] op_sel:[1,0,0]
	v_pk_fma_f32 v[82:83], v[82:83], v[68:69], v[72:73] op_sel:[1,0,0]
	ds_read_b128 v[68:71], v106 offset:256
	ds_read_b128 v[120:123], v106 offset:320
	s_waitcnt lgkmcnt(1)
	v_mfma_f32_16x16x32_bf16 v[108:111], v[2:5], v[68:71], 0
	v_mfma_f32_16x16x32_bf16 v[112:115], v[10:13], v[68:71], 0
	v_mfma_f32_16x16x32_bf16 v[116:119], v[18:21], v[68:71], 0
	v_mfma_f32_16x16x32_bf16 v[68:71], v[26:29], v[68:71], 0
	s_waitcnt lgkmcnt(0)
	v_mfma_f32_16x16x32_bf16 v[108:111], v[6:9], v[120:123], v[108:111]
	v_mfma_f32_16x16x32_bf16 v[112:115], v[14:17], v[120:123], v[112:115]
	v_mfma_f32_16x16x32_bf16 v[116:119], v[22:25], v[120:123], v[116:119]
	s_nop 1
	v_mfma_f32_16x16x32_bf16 v[120:123], v[30:33], v[120:123], v[68:71]
	s_nop 5
	v_max_f32_e32 v72, 0, v114
	v_max_f32_e32 v68, 0, v108
	v_max_f32_e32 v69, 0, v109
	v_max_f32_e32 v70, 0, v110
	v_max_f32_e32 v71, 0, v111
	v_max_f32_e32 v73, 0, v115
	v_pk_fma_f32 v[66:67], v[68:69], v[84:85], v[66:67] op_sel_hi:[1,0,1]
	v_pk_fma_f32 v[68:69], v[70:71], v[84:85], v[78:79] op_sel_hi:[1,0,1]
	v_pk_fma_f32 v[72:73], v[72:73], v[84:85], v[80:81] op_sel_hi:[1,0,1]
	v_max_f32_e32 v76, 0, v116
	v_max_f32_e32 v77, 0, v117
	v_max_f32_e32 v78, 0, v118
	v_max_f32_e32 v79, 0, v119
	v_max_f32_e32 v80, 0, v122
	v_max_f32_e32 v81, 0, v123
	v_pk_fma_f32 v[74:75], v[84:85], v[76:77], v[74:75] op_sel_hi:[0,1,1]
	v_pk_fma_f32 v[76:77], v[84:85], v[78:79], v[92:93] op_sel_hi:[0,1,1]
	v_pk_fma_f32 v[80:81], v[84:85], v[80:81], v[94:95] op_sel_hi:[0,1,1]
	ds_read_b128 v[92:95], v106 offset:384
	v_max_f32_e32 v78, 0, v120
	v_max_f32_e32 v79, 0, v121
	ds_read_b128 v[120:123], v106 offset:448
	s_waitcnt lgkmcnt(1)
	v_mfma_f32_16x16x32_bf16 v[108:111], v[2:5], v[92:95], 0
	v_max_f32_e32 v71, 0, v113
	v_max_f32_e32 v70, 0, v112
	v_mfma_f32_16x16x32_bf16 v[112:115], v[10:13], v[92:95], 0
	s_waitcnt lgkmcnt(0)
	v_mfma_f32_16x16x32_bf16 v[108:111], v[6:9], v[120:123], v[108:111]
	v_fma_f32 v70, v70, v84, v96
	v_fma_f32 v71, v71, v84, v97
	v_pk_fma_f32 v[78:79], v[84:85], v[78:79], v[82:83] op_sel_hi:[0,1,1]
	v_add_u32_e32 v106, 0x200, v106
	v_mfma_f32_16x16x32_bf16 v[116:119], v[18:21], v[92:95], 0
	v_mfma_f32_16x16x32_bf16 v[112:115], v[14:17], v[120:123], v[112:115]
	s_nop 1
	v_mfma_f32_16x16x32_bf16 v[92:95], v[26:29], v[92:95], 0
	v_max_f32_e32 v96, 0, v110
	v_max_f32_e32 v82, 0, v108
	v_mfma_f32_16x16x32_bf16 v[116:119], v[22:25], v[120:123], v[116:119]
	v_max_f32_e32 v83, 0, v109
	v_max_f32_e32 v97, 0, v111
	v_mov_b32_e32 v84, v85
	v_pk_fma_f32 v[68:69], v[96:97], v[84:85], v[68:69] op_sel_hi:[1,0,1]
	v_pk_fma_f32 v[66:67], v[82:83], v[84:85], v[66:67] op_sel_hi:[1,0,1]
	v_max_f32_e32 v96, 0, v114
	v_mfma_f32_16x16x32_bf16 v[92:95], v[30:33], v[120:123], v[92:95]
	v_max_f32_e32 v82, 0, v112
	v_max_f32_e32 v83, 0, v113
	v_max_f32_e32 v97, 0, v115
	v_pk_fma_f32 v[72:73], v[96:97], v[84:85], v[72:73] op_sel_hi:[1,0,1]
	v_pk_fma_f32 v[70:71], v[82:83], v[84:85], v[70:71] op_sel_hi:[1,0,1]
	v_max_f32_e32 v96, 0, v118
	v_max_f32_e32 v82, 0, v116
	v_max_f32_e32 v83, 0, v117
	v_max_f32_e32 v97, 0, v119
	v_pk_fma_f32 v[76:77], v[84:85], v[96:97], v[76:77] op_sel_hi:[0,1,1]
	v_pk_fma_f32 v[74:75], v[84:85], v[82:83], v[74:75] op_sel_hi:[0,1,1]
	v_max_f32_e32 v82, 0, v92
	v_max_f32_e32 v92, 0, v94
	v_max_f32_e32 v83, 0, v93
	v_max_f32_e32 v93, 0, v95
	v_pk_fma_f32 v[80:81], v[84:85], v[92:93], v[80:81] op_sel_hi:[0,1,1]
	v_pk_fma_f32 v[78:79], v[84:85], v[82:83], v[78:79] op_sel_hi:[0,1,1]
	s_cbranch_scc0 .LBB0_320
; #define MFMA16(a, b, c) __builtin_amdgcn_mfma_f32_16x16x32_bf16((a), (b), (c), 0, 0, 0)
; DI void indexer_item(const Params& p, int b, int qt16, char* smem) {
;     ...
; #pragma unroll
;     for (int t = 0; t < 4; ++t)
; #pragma unroll
;       for (int ks = 0; ks < 2; ++ks) kf[t][ks] = kfn[t][ks];
;     if (kb + 8 < nkb) {
; #pragma unroll
;       for (int t = 0; t < 4; ++t)
; #pragma unroll
;         for (int ks = 0; ks < 2; ++ks)
;           kfn[t][ks] = *(const bf16x8*)(base + (long)((kb + 8) * 64 + t * 16 + l15) * PW + DIK + ks * 32 + g4 * 8);
;     }
;     f32x4 isc[4];
; #pragma unroll
;     for (int t = 0; t < 4; ++t) isc[t] = f32x4{0.f, 0.f, 0.f, 0.f};
; #pragma unroll 4
;     for (int h = 0; h < 16; ++h) {
;       f32x4 acc[4];
; #pragma unroll
;       for (int t = 0; t < 4; ++t) acc[t] = f32x4{0.f, 0.f, 0.f, 0.f};
; #pragma unroll
;       for (int ks = 0; ks < 2; ++ks) {
;         const bf16x8 bq = *(const bf16x8*)(iqs + l15 * 1040 + h * 64 + ks * 32 + g4 * 8);
; #pragma unroll
;         for (int t = 0; t < 4; ++t) acc[t] = MFMA16(kf[t][ks], bq, acc[t]);
;       }
;       const float w = wls[l15 * 16 + h];
; #pragma unroll
;       for (int t = 0; t < 4; ++t)
; #pragma unroll
;         for (int i = 0; i < 4; ++i) isc[t][i] += fmaxf(acc[t][i], 0.f) * w;
;     }
; #pragma unroll
;     for (int t = 0; t < 4; ++t) *(f32x4*)(scr + (long)l15 * SEQ + kb * 64 + t * 16 + g4 * 4) = isc[t];
	v_lshlrev_b32_e32 v2, 6, v104
	v_ashrrev_i32_e32 v3, 31, v2
	v_lshl_add_u64 v[2:3], v[2:3], 2, v[90:91]
	global_store_dwordx4 v[2:3], v[66:69], off
	global_store_dwordx4 v[2:3], v[70:73], off offset:64
	global_store_dwordx4 v[2:3], v[74:77], off offset:128
	global_store_dwordx4 v[2:3], v[78:81], off offset:192
	s_waitcnt vmcnt(11)
	v_mov_b64_e32 v[2:3], v[34:35]
	s_waitcnt vmcnt(10)
	v_mov_b64_e32 v[6:7], v[38:39]
	s_waitcnt vmcnt(9)
	v_mov_b64_e32 v[10:11], v[42:43]
	s_waitcnt vmcnt(8)
	v_mov_b64_e32 v[14:15], v[46:47]
	s_waitcnt vmcnt(7)
	v_mov_b64_e32 v[18:19], v[50:51]
	s_waitcnt vmcnt(6)
	v_mov_b64_e32 v[22:23], v[54:55]
	s_waitcnt vmcnt(5)
	v_mov_b64_e32 v[26:27], v[58:59]
	s_waitcnt vmcnt(4)
	v_mov_b64_e32 v[30:31], v[62:63]
	v_mov_b64_e32 v[4:5], v[36:37]
	v_mov_b64_e32 v[8:9], v[40:41]
	v_mov_b64_e32 v[12:13], v[44:45]
	v_mov_b64_e32 v[16:17], v[48:49]
	v_mov_b64_e32 v[20:21], v[52:53]
	v_mov_b64_e32 v[24:25], v[56:57]
	v_mov_b64_e32 v[28:29], v[60:61]
	v_mov_b64_e32 v[32:33], v[64:65]
	v_mov_b32_e32 v104, v105
	s_andn2_b64 exec, exec, s[4:5]
	s_cbranch_execnz .LBB0_317
